# logits via f32 MFMA 16x16x4 + GEMM loop LDS-DMA saddr addressing
# speedup vs baseline: 1.0128x; 1.0128x over previous
; __global__ void __launch_bounds__(NWAVES * 64, 2) fwd_megakernel(Args args) {
;     ...
;             for (int jj = 0; jj < 4; ++jj) { const f32x4 a = *(const f32x4*)(wf + (size_t)wave * DM + 512 * jj + 8 * ln), bq = *(const f32x4*)(wf + (size_t)wave * DM + 512 * jj + 8 * ln + 4);
; #pragma unroll
;                 for (int e = 0; e < 4; ++e) { wreg[8 * jj + e] = a[e]; wreg[8 * jj + 4 + e] = bq[e]; } }
;             const float bf = args.in[8][wave];
;             for (int m0 = vcu2 * 4; m0 < M; m0 += G * 4) {
;                 u32x4 pw[4][4]; float sq[4];
; #pragma unroll
;                 for (int q = 0; q < 4; ++q) { sq[q] = ss[M + m0 + q];
; #pragma unroll
;                     for (int jj = 0; jj < 4; ++jj) pw[q][jj] = *(const u32x4*)(XB + (size_t)(m0 + q) * DM + 512 * jj + 8 * ln); }
; #pragma unroll
;                 for (int q = 0; q < 4; ++q) { float d = 0.f;
; #pragma unroll
;                     for (int jj = 0; jj < 4; ++jj) { const u32x4 w = pw[q][jj];
;                         d += __uint_as_float(w.x << 16) * wreg[8 * jj + 0] + __uint_as_float(w.x & 0xffff0000u) * wreg[8 * jj + 1] + __uint_as_float(w.y << 16) * wreg[8 * jj + 2] + __uint_as_float(w.y & 0xffff0000u) * wreg[8 * jj + 3]
;                            + __uint_as_float(w.z << 16) * wreg[8 * jj + 4] + __uint_as_float(w.z & 0xffff0000u) * wreg[8 * jj + 5] + __uint_as_float(w.w << 16) * wreg[8 * jj + 6] + __uint_as_float(w.w & 0xffff0000u) * wreg[8 * jj + 7]; }
.LBB0_591:
	s_and_b64 vcc, exec, s[4:5]
	s_cbranch_vccz .LBB0_605
	s_cmp_gt_i32 s39, 1
	s_cbranch_scc0 .LBB0_606
	s_cmp_lt_i32 s39, 3
	s_mov_b64 s[4:5], -1
	s_cbranch_scc0 .LBB0_607
	v_lshrrev_b32_e32 v0, 6, v166
	v_readlane_b32 s4, v249, 1
	v_readfirstlane_b32 s12, v0
	s_lshl_b32 s4, s4, 4
	s_and_b32 s13, s12, 3
	s_lshr_b32 s14, s12, 2
	s_cmpk_gt_i32 s4, 0x3fff
	s_cbranch_scc1 .Llg_done
	v_and_b32_e32 v0, 15, v168
	v_lshrrev_b32_e32 v4, 4, v168
	v_lshlrev_b32_e32 v5, 12, v0
	v_lshl_or_b32 v2, v4, 5, v5
	v_and_b32_e32 v5, 7, v168
	v_lshlrev_b32_e32 v5, 13, v5
	v_lshl_or_b32 v3, v4, 6, v5
	s_lshl_b32 s5, s14, 12
	s_add_u32 s5, s5, 0x100000
	s_add_u32 s8, s60, s5
	s_addc_u32 s9, s61, 0
	v_readlane_b32 s16, v250, 63
	v_readlane_b32 s17, v249, 0
	s_lshl_b32 s5, s12, 2
	s_sub_u32 s16, s16, s5
	s_subb_u32 s17, s17, 0
	s_mov_b32 s18, 0xbfb8aa3b
	s_mov_b32 s19, 0x3f317218
.Llg_trip:
	s_lshl_b32 s5, s4, 12
	s_lshl_b32 s1, s13, 16
	s_add_u32 s5, s5, s1
	s_lshl_b32 s1, s14, 11
	s_add_u32 s5, s5, s1
	s_add_u32 s6, s94, s5
	s_addc_u32 s7, s95, 0
	v_mov_b32_e32 v4, 0
	v_mov_b32_e32 v5, 0
	v_mov_b32_e32 v6, 0
	v_mov_b32_e32 v7, 0
	v_mov_b32_e32 v8, 0
	v_mov_b32_e32 v9, 0
	v_mov_b32_e32 v10, 0
	v_mov_b32_e32 v11, 0
	global_load_dwordx4 v[28:31], v2, s[6:7] offset:0
	global_load_dwordx4 v[32:35], v2, s[6:7] offset:16
	global_load_dwordx4 v[36:39], v2, s[6:7] offset:128
	global_load_dwordx4 v[40:43], v2, s[6:7] offset:144
	global_load_dwordx4 v[44:47], v2, s[6:7] offset:256
	global_load_dwordx4 v[48:51], v2, s[6:7] offset:272
	global_load_dwordx4 v[52:55], v2, s[6:7] offset:384
	global_load_dwordx4 v[56:59], v2, s[6:7] offset:400
	global_load_dwordx4 v[60:63], v2, s[6:7] offset:512
	global_load_dwordx4 v[64:67], v2, s[6:7] offset:528
	global_load_dwordx4 v[76:79], v3, s[8:9] offset:0
	global_load_dwordx4 v[80:83], v3, s[8:9] offset:16
	global_load_dwordx4 v[84:87], v3, s[8:9] offset:32
	global_load_dwordx4 v[88:91], v3, s[8:9] offset:48
	global_load_dwordx4 v[92:95], v3, s[8:9] offset:256
	global_load_dwordx4 v[96:99], v3, s[8:9] offset:272
	global_load_dwordx4 v[100:103], v3, s[8:9] offset:288
	global_load_dwordx4 v[104:107], v3, s[8:9] offset:304
	s_waitcnt vmcnt(16)
	v_lshlrev_b32_e32 v12, 16, v28
	v_and_b32_e32 v28, 0xffff0000, v28
	v_lshlrev_b32_e32 v13, 16, v29
	v_and_b32_e32 v29, 0xffff0000, v29
	v_lshlrev_b32_e32 v14, 16, v30
	v_and_b32_e32 v30, 0xffff0000, v30
	v_lshlrev_b32_e32 v15, 16, v31
	v_and_b32_e32 v31, 0xffff0000, v31
	v_lshlrev_b32_e32 v16, 16, v32
	v_and_b32_e32 v32, 0xffff0000, v32
	v_lshlrev_b32_e32 v17, 16, v33
	v_and_b32_e32 v33, 0xffff0000, v33
	v_lshlrev_b32_e32 v18, 16, v34
	v_and_b32_e32 v34, 0xffff0000, v34
	v_lshlrev_b32_e32 v19, 16, v35
	v_and_b32_e32 v35, 0xffff0000, v35
	global_load_dwordx4 v[68:71], v2, s[6:7] offset:640
	global_load_dwordx4 v[72:75], v2, s[6:7] offset:656
	global_load_dwordx4 v[108:111], v3, s[8:9] offset:512
	global_load_dwordx4 v[112:115], v3, s[8:9] offset:528
	global_load_dwordx4 v[116:119], v3, s[8:9] offset:544
	global_load_dwordx4 v[120:123], v3, s[8:9] offset:560
	s_waitcnt vmcnt(10)
	v_mfma_f32_16x16x4_f32 v[4:7], v12, v76, v[4:7]
	v_lshlrev_b32_e32 v20, 16, v36
	v_mfma_f32_16x16x4_f32 v[8:11], v28, v77, v[8:11]
	v_and_b32_e32 v36, 0xffff0000, v36
	v_mfma_f32_16x16x4_f32 v[4:7], v13, v78, v[4:7]
	v_lshlrev_b32_e32 v21, 16, v37
	v_mfma_f32_16x16x4_f32 v[8:11], v29, v79, v[8:11]
	v_and_b32_e32 v37, 0xffff0000, v37
	v_mfma_f32_16x16x4_f32 v[4:7], v14, v80, v[4:7]
	v_lshlrev_b32_e32 v22, 16, v38
	v_mfma_f32_16x16x4_f32 v[8:11], v30, v81, v[8:11]
	v_and_b32_e32 v38, 0xffff0000, v38
	v_mfma_f32_16x16x4_f32 v[4:7], v15, v82, v[4:7]
	v_lshlrev_b32_e32 v23, 16, v39
	v_mfma_f32_16x16x4_f32 v[8:11], v31, v83, v[8:11]
	v_and_b32_e32 v39, 0xffff0000, v39
	v_mfma_f32_16x16x4_f32 v[4:7], v16, v84, v[4:7]
	v_lshlrev_b32_e32 v24, 16, v40
	v_mfma_f32_16x16x4_f32 v[8:11], v32, v85, v[8:11]
	v_and_b32_e32 v40, 0xffff0000, v40
	v_mfma_f32_16x16x4_f32 v[4:7], v17, v86, v[4:7]
	v_lshlrev_b32_e32 v25, 16, v41
	v_mfma_f32_16x16x4_f32 v[8:11], v33, v87, v[8:11]
	v_and_b32_e32 v41, 0xffff0000, v41
	v_mfma_f32_16x16x4_f32 v[4:7], v18, v88, v[4:7]
	v_lshlrev_b32_e32 v26, 16, v42
	v_mfma_f32_16x16x4_f32 v[8:11], v34, v89, v[8:11]
	v_and_b32_e32 v42, 0xffff0000, v42
	v_mfma_f32_16x16x4_f32 v[4:7], v19, v90, v[4:7]
	v_lshlrev_b32_e32 v27, 16, v43
	v_mfma_f32_16x16x4_f32 v[8:11], v35, v91, v[8:11]
	v_and_b32_e32 v43, 0xffff0000, v43
	global_load_dwordx4 v[28:31], v2, s[6:7] offset:768
	global_load_dwordx4 v[32:35], v2, s[6:7] offset:784
	global_load_dwordx4 v[76:79], v3, s[8:9] offset:768
	global_load_dwordx4 v[80:83], v3, s[8:9] offset:784
	global_load_dwordx4 v[84:87], v3, s[8:9] offset:800
	global_load_dwordx4 v[88:91], v3, s[8:9] offset:816
	s_waitcnt vmcnt(12)
	v_mfma_f32_16x16x4_f32 v[4:7], v20, v92, v[4:7]
	v_lshlrev_b32_e32 v12, 16, v44
	v_mfma_f32_16x16x4_f32 v[8:11], v36, v93, v[8:11]
	v_and_b32_e32 v44, 0xffff0000, v44
	v_mfma_f32_16x16x4_f32 v[4:7], v21, v94, v[4:7]
	v_lshlrev_b32_e32 v13, 16, v45
	v_mfma_f32_16x16x4_f32 v[8:11], v37, v95, v[8:11]
	v_and_b32_e32 v45, 0xffff0000, v45
	v_mfma_f32_16x16x4_f32 v[4:7], v22, v96, v[4:7]
	v_lshlrev_b32_e32 v14, 16, v46
	v_mfma_f32_16x16x4_f32 v[8:11], v38, v97, v[8:11]
	v_and_b32_e32 v46, 0xffff0000, v46
	v_mfma_f32_16x16x4_f32 v[4:7], v23, v98, v[4:7]
	v_lshlrev_b32_e32 v15, 16, v47
	v_mfma_f32_16x16x4_f32 v[8:11], v39, v99, v[8:11]
	v_and_b32_e32 v47, 0xffff0000, v47
	v_mfma_f32_16x16x4_f32 v[4:7], v24, v100, v[4:7]
	v_lshlrev_b32_e32 v16, 16, v48
	v_mfma_f32_16x16x4_f32 v[8:11], v40, v101, v[8:11]
	v_and_b32_e32 v48, 0xffff0000, v48
	v_mfma_f32_16x16x4_f32 v[4:7], v25, v102, v[4:7]
	v_lshlrev_b32_e32 v17, 16, v49
	v_mfma_f32_16x16x4_f32 v[8:11], v41, v103, v[8:11]
	v_and_b32_e32 v49, 0xffff0000, v49
	v_mfma_f32_16x16x4_f32 v[4:7], v26, v104, v[4:7]
	v_lshlrev_b32_e32 v18, 16, v50
	v_mfma_f32_16x16x4_f32 v[8:11], v42, v105, v[8:11]
	v_and_b32_e32 v50, 0xffff0000, v50
	v_mfma_f32_16x16x4_f32 v[4:7], v27, v106, v[4:7]
	v_lshlrev_b32_e32 v19, 16, v51
	v_mfma_f32_16x16x4_f32 v[8:11], v43, v107, v[8:11]
	v_and_b32_e32 v51, 0xffff0000, v51
	global_load_dwordx4 v[36:39], v2, s[6:7] offset:896
	global_load_dwordx4 v[40:43], v2, s[6:7] offset:912
	global_load_dwordx4 v[92:95], v3, s[8:9] offset:1024
	global_load_dwordx4 v[96:99], v3, s[8:9] offset:1040
	global_load_dwordx4 v[100:103], v3, s[8:9] offset:1056
	global_load_dwordx4 v[104:107], v3, s[8:9] offset:1072
	s_waitcnt vmcnt(12)
; __global__ void __launch_bounds__(NWAVES * 64, 2) fwd_megakernel(Args args) {
;     ...
;                 for (int q = 0; q < 4; ++q) { float d = 0.f;
; #pragma unroll
;                     for (int jj = 0; jj < 4; ++jj) { const u32x4 w = pw[q][jj];
;                         d += __uint_as_float(w.x << 16) * wreg[8 * jj + 0] + __uint_as_float(w.x & 0xffff0000u) * wreg[8 * jj + 1] + __uint_as_float(w.y << 16) * wreg[8 * jj + 2] + __uint_as_float(w.y & 0xffff0000u) * wreg[8 * jj + 3]
;                            + __uint_as_float(w.z << 16) * wreg[8 * jj + 4] + __uint_as_float(w.z & 0xffff0000u) * wreg[8 * jj + 5] + __uint_as_float(w.w << 16) * wreg[8 * jj + 6] + __uint_as_float(w.w & 0xffff0000u) * wreg[8 * jj + 7]; }
	v_mfma_f32_16x16x4_f32 v[4:7], v12, v108, v[4:7]
	v_lshlrev_b32_e32 v20, 16, v52
	v_mfma_f32_16x16x4_f32 v[8:11], v44, v109, v[8:11]
	v_and_b32_e32 v52, 0xffff0000, v52
	v_mfma_f32_16x16x4_f32 v[4:7], v13, v110, v[4:7]
	v_lshlrev_b32_e32 v21, 16, v53
	v_mfma_f32_16x16x4_f32 v[8:11], v45, v111, v[8:11]
	v_and_b32_e32 v53, 0xffff0000, v53
	v_mfma_f32_16x16x4_f32 v[4:7], v14, v112, v[4:7]
	v_lshlrev_b32_e32 v22, 16, v54
	v_mfma_f32_16x16x4_f32 v[8:11], v46, v113, v[8:11]
	v_and_b32_e32 v54, 0xffff0000, v54
	v_mfma_f32_16x16x4_f32 v[4:7], v15, v114, v[4:7]
	v_lshlrev_b32_e32 v23, 16, v55
	v_mfma_f32_16x16x4_f32 v[8:11], v47, v115, v[8:11]
	v_and_b32_e32 v55, 0xffff0000, v55
	v_mfma_f32_16x16x4_f32 v[4:7], v16, v116, v[4:7]
	v_lshlrev_b32_e32 v24, 16, v56
	v_mfma_f32_16x16x4_f32 v[8:11], v48, v117, v[8:11]
	v_and_b32_e32 v56, 0xffff0000, v56
	v_mfma_f32_16x16x4_f32 v[4:7], v17, v118, v[4:7]
	v_lshlrev_b32_e32 v25, 16, v57
	v_mfma_f32_16x16x4_f32 v[8:11], v49, v119, v[8:11]
	v_and_b32_e32 v57, 0xffff0000, v57
	v_mfma_f32_16x16x4_f32 v[4:7], v18, v120, v[4:7]
	v_lshlrev_b32_e32 v26, 16, v58
	v_mfma_f32_16x16x4_f32 v[8:11], v50, v121, v[8:11]
	v_and_b32_e32 v58, 0xffff0000, v58
	v_mfma_f32_16x16x4_f32 v[4:7], v19, v122, v[4:7]
	v_lshlrev_b32_e32 v27, 16, v59
	v_mfma_f32_16x16x4_f32 v[8:11], v51, v123, v[8:11]
	v_and_b32_e32 v59, 0xffff0000, v59
	global_load_dwordx4 v[44:47], v2, s[6:7] offset:1024
	global_load_dwordx4 v[48:51], v2, s[6:7] offset:1040
	global_load_dwordx4 v[108:111], v3, s[8:9] offset:1280
	global_load_dwordx4 v[112:115], v3, s[8:9] offset:1296
	global_load_dwordx4 v[116:119], v3, s[8:9] offset:1312
	global_load_dwordx4 v[120:123], v3, s[8:9] offset:1328
	s_waitcnt vmcnt(12)
	v_mfma_f32_16x16x4_f32 v[4:7], v20, v76, v[4:7]
	v_lshlrev_b32_e32 v12, 16, v60
	v_mfma_f32_16x16x4_f32 v[8:11], v52, v77, v[8:11]
	v_and_b32_e32 v60, 0xffff0000, v60
	v_mfma_f32_16x16x4_f32 v[4:7], v21, v78, v[4:7]
	v_lshlrev_b32_e32 v13, 16, v61
	v_mfma_f32_16x16x4_f32 v[8:11], v53, v79, v[8:11]
	v_and_b32_e32 v61, 0xffff0000, v61
	v_mfma_f32_16x16x4_f32 v[4:7], v22, v80, v[4:7]
	v_lshlrev_b32_e32 v14, 16, v62
	v_mfma_f32_16x16x4_f32 v[8:11], v54, v81, v[8:11]
	v_and_b32_e32 v62, 0xffff0000, v62
	v_mfma_f32_16x16x4_f32 v[4:7], v23, v82, v[4:7]
	v_lshlrev_b32_e32 v15, 16, v63
	v_mfma_f32_16x16x4_f32 v[8:11], v55, v83, v[8:11]
	v_and_b32_e32 v63, 0xffff0000, v63
	v_mfma_f32_16x16x4_f32 v[4:7], v24, v84, v[4:7]
	v_lshlrev_b32_e32 v16, 16, v64
	v_mfma_f32_16x16x4_f32 v[8:11], v56, v85, v[8:11]
	v_and_b32_e32 v64, 0xffff0000, v64
	v_mfma_f32_16x16x4_f32 v[4:7], v25, v86, v[4:7]
	v_lshlrev_b32_e32 v17, 16, v65
	v_mfma_f32_16x16x4_f32 v[8:11], v57, v87, v[8:11]
	v_and_b32_e32 v65, 0xffff0000, v65
	v_mfma_f32_16x16x4_f32 v[4:7], v26, v88, v[4:7]
	v_lshlrev_b32_e32 v18, 16, v66
	v_mfma_f32_16x16x4_f32 v[8:11], v58, v89, v[8:11]
	v_and_b32_e32 v66, 0xffff0000, v66
	v_mfma_f32_16x16x4_f32 v[4:7], v27, v90, v[4:7]
	v_lshlrev_b32_e32 v19, 16, v67
	v_mfma_f32_16x16x4_f32 v[8:11], v59, v91, v[8:11]
	v_and_b32_e32 v67, 0xffff0000, v67
	global_load_dwordx4 v[52:55], v2, s[6:7] offset:1152
	global_load_dwordx4 v[56:59], v2, s[6:7] offset:1168
	global_load_dwordx4 v[76:79], v3, s[8:9] offset:1536
	global_load_dwordx4 v[80:83], v3, s[8:9] offset:1552
	global_load_dwordx4 v[84:87], v3, s[8:9] offset:1568
	global_load_dwordx4 v[88:91], v3, s[8:9] offset:1584
	s_waitcnt vmcnt(12)
	v_mfma_f32_16x16x4_f32 v[4:7], v12, v92, v[4:7]
	v_lshlrev_b32_e32 v20, 16, v68
	v_mfma_f32_16x16x4_f32 v[8:11], v60, v93, v[8:11]
	v_and_b32_e32 v68, 0xffff0000, v68
	v_mfma_f32_16x16x4_f32 v[4:7], v13, v94, v[4:7]
	v_lshlrev_b32_e32 v21, 16, v69
	v_mfma_f32_16x16x4_f32 v[8:11], v61, v95, v[8:11]
	v_and_b32_e32 v69, 0xffff0000, v69
	v_mfma_f32_16x16x4_f32 v[4:7], v14, v96, v[4:7]
	v_lshlrev_b32_e32 v22, 16, v70
	v_mfma_f32_16x16x4_f32 v[8:11], v62, v97, v[8:11]
	v_and_b32_e32 v70, 0xffff0000, v70
	v_mfma_f32_16x16x4_f32 v[4:7], v15, v98, v[4:7]
	v_lshlrev_b32_e32 v23, 16, v71
	v_mfma_f32_16x16x4_f32 v[8:11], v63, v99, v[8:11]
	v_and_b32_e32 v71, 0xffff0000, v71
	v_mfma_f32_16x16x4_f32 v[4:7], v16, v100, v[4:7]
	v_lshlrev_b32_e32 v24, 16, v72
	v_mfma_f32_16x16x4_f32 v[8:11], v64, v101, v[8:11]
	v_and_b32_e32 v72, 0xffff0000, v72
	v_mfma_f32_16x16x4_f32 v[4:7], v17, v102, v[4:7]
	v_lshlrev_b32_e32 v25, 16, v73
	v_mfma_f32_16x16x4_f32 v[8:11], v65, v103, v[8:11]
	v_and_b32_e32 v73, 0xffff0000, v73
	v_mfma_f32_16x16x4_f32 v[4:7], v18, v104, v[4:7]
	v_lshlrev_b32_e32 v26, 16, v74
	v_mfma_f32_16x16x4_f32 v[8:11], v66, v105, v[8:11]
	v_and_b32_e32 v74, 0xffff0000, v74
	v_mfma_f32_16x16x4_f32 v[4:7], v19, v106, v[4:7]
	v_lshlrev_b32_e32 v27, 16, v75
	v_mfma_f32_16x16x4_f32 v[8:11], v67, v107, v[8:11]
	v_and_b32_e32 v75, 0xffff0000, v75
	global_load_dwordx4 v[60:63], v2, s[6:7] offset:1280
	global_load_dwordx4 v[64:67], v2, s[6:7] offset:1296
	global_load_dwordx4 v[92:95], v3, s[8:9] offset:1792
	global_load_dwordx4 v[96:99], v3, s[8:9] offset:1808
	global_load_dwordx4 v[100:103], v3, s[8:9] offset:1824
	global_load_dwordx4 v[104:107], v3, s[8:9] offset:1840
	s_waitcnt vmcnt(12)
; __global__ void __launch_bounds__(NWAVES * 64, 2) fwd_megakernel(Args args) {
;     ...
;                 for (int q = 0; q < 4; ++q) { float d = 0.f;
; #pragma unroll
;                     for (int jj = 0; jj < 4; ++jj) { const u32x4 w = pw[q][jj];
;                         d += __uint_as_float(w.x << 16) * wreg[8 * jj + 0] + __uint_as_float(w.x & 0xffff0000u) * wreg[8 * jj + 1] + __uint_as_float(w.y << 16) * wreg[8 * jj + 2] + __uint_as_float(w.y & 0xffff0000u) * wreg[8 * jj + 3]
;                            + __uint_as_float(w.z << 16) * wreg[8 * jj + 4] + __uint_as_float(w.z & 0xffff0000u) * wreg[8 * jj + 5] + __uint_as_float(w.w << 16) * wreg[8 * jj + 6] + __uint_as_float(w.w & 0xffff0000u) * wreg[8 * jj + 7]; }
	v_mfma_f32_16x16x4_f32 v[4:7], v20, v108, v[4:7]
	v_lshlrev_b32_e32 v12, 16, v28
	v_mfma_f32_16x16x4_f32 v[8:11], v68, v109, v[8:11]
	v_and_b32_e32 v28, 0xffff0000, v28
	v_mfma_f32_16x16x4_f32 v[4:7], v21, v110, v[4:7]
	v_lshlrev_b32_e32 v13, 16, v29
	v_mfma_f32_16x16x4_f32 v[8:11], v69, v111, v[8:11]
	v_and_b32_e32 v29, 0xffff0000, v29
	v_mfma_f32_16x16x4_f32 v[4:7], v22, v112, v[4:7]
	v_lshlrev_b32_e32 v14, 16, v30
	v_mfma_f32_16x16x4_f32 v[8:11], v70, v113, v[8:11]
	v_and_b32_e32 v30, 0xffff0000, v30
	v_mfma_f32_16x16x4_f32 v[4:7], v23, v114, v[4:7]
	v_lshlrev_b32_e32 v15, 16, v31
	v_mfma_f32_16x16x4_f32 v[8:11], v71, v115, v[8:11]
	v_and_b32_e32 v31, 0xffff0000, v31
	v_mfma_f32_16x16x4_f32 v[4:7], v24, v116, v[4:7]
	v_lshlrev_b32_e32 v16, 16, v32
	v_mfma_f32_16x16x4_f32 v[8:11], v72, v117, v[8:11]
	v_and_b32_e32 v32, 0xffff0000, v32
	v_mfma_f32_16x16x4_f32 v[4:7], v25, v118, v[4:7]
	v_lshlrev_b32_e32 v17, 16, v33
	v_mfma_f32_16x16x4_f32 v[8:11], v73, v119, v[8:11]
	v_and_b32_e32 v33, 0xffff0000, v33
	v_mfma_f32_16x16x4_f32 v[4:7], v26, v120, v[4:7]
	v_lshlrev_b32_e32 v18, 16, v34
	v_mfma_f32_16x16x4_f32 v[8:11], v74, v121, v[8:11]
	v_and_b32_e32 v34, 0xffff0000, v34
	v_mfma_f32_16x16x4_f32 v[4:7], v27, v122, v[4:7]
	v_lshlrev_b32_e32 v19, 16, v35
	v_mfma_f32_16x16x4_f32 v[8:11], v75, v123, v[8:11]
	v_and_b32_e32 v35, 0xffff0000, v35
	global_load_dwordx4 v[68:71], v2, s[6:7] offset:1408
	global_load_dwordx4 v[72:75], v2, s[6:7] offset:1424
	global_load_dwordx4 v[108:111], v3, s[8:9] offset:2048
	global_load_dwordx4 v[112:115], v3, s[8:9] offset:2064
	global_load_dwordx4 v[116:119], v3, s[8:9] offset:2080
	global_load_dwordx4 v[120:123], v3, s[8:9] offset:2096
	s_waitcnt vmcnt(12)
	v_mfma_f32_16x16x4_f32 v[4:7], v12, v76, v[4:7]
	v_lshlrev_b32_e32 v20, 16, v36
	v_mfma_f32_16x16x4_f32 v[8:11], v28, v77, v[8:11]
	v_and_b32_e32 v36, 0xffff0000, v36
	v_mfma_f32_16x16x4_f32 v[4:7], v13, v78, v[4:7]
	v_lshlrev_b32_e32 v21, 16, v37
	v_mfma_f32_16x16x4_f32 v[8:11], v29, v79, v[8:11]
	v_and_b32_e32 v37, 0xffff0000, v37
	v_mfma_f32_16x16x4_f32 v[4:7], v14, v80, v[4:7]
	v_lshlrev_b32_e32 v22, 16, v38
	v_mfma_f32_16x16x4_f32 v[8:11], v30, v81, v[8:11]
	v_and_b32_e32 v38, 0xffff0000, v38
	v_mfma_f32_16x16x4_f32 v[4:7], v15, v82, v[4:7]
	v_lshlrev_b32_e32 v23, 16, v39
	v_mfma_f32_16x16x4_f32 v[8:11], v31, v83, v[8:11]
	v_and_b32_e32 v39, 0xffff0000, v39
	v_mfma_f32_16x16x4_f32 v[4:7], v16, v84, v[4:7]
	v_lshlrev_b32_e32 v24, 16, v40
	v_mfma_f32_16x16x4_f32 v[8:11], v32, v85, v[8:11]
	v_and_b32_e32 v40, 0xffff0000, v40
	v_mfma_f32_16x16x4_f32 v[4:7], v17, v86, v[4:7]
	v_lshlrev_b32_e32 v25, 16, v41
	v_mfma_f32_16x16x4_f32 v[8:11], v33, v87, v[8:11]
	v_and_b32_e32 v41, 0xffff0000, v41
	v_mfma_f32_16x16x4_f32 v[4:7], v18, v88, v[4:7]
	v_lshlrev_b32_e32 v26, 16, v42
	v_mfma_f32_16x16x4_f32 v[8:11], v34, v89, v[8:11]
	v_and_b32_e32 v42, 0xffff0000, v42
	v_mfma_f32_16x16x4_f32 v[4:7], v19, v90, v[4:7]
	v_lshlrev_b32_e32 v27, 16, v43
	v_mfma_f32_16x16x4_f32 v[8:11], v35, v91, v[8:11]
	v_and_b32_e32 v43, 0xffff0000, v43
	global_load_dwordx4 v[28:31], v2, s[6:7] offset:1536
	global_load_dwordx4 v[32:35], v2, s[6:7] offset:1552
	global_load_dwordx4 v[76:79], v3, s[8:9] offset:2304
	global_load_dwordx4 v[80:83], v3, s[8:9] offset:2320
	global_load_dwordx4 v[84:87], v3, s[8:9] offset:2336
	global_load_dwordx4 v[88:91], v3, s[8:9] offset:2352
	s_waitcnt vmcnt(12)
	v_mfma_f32_16x16x4_f32 v[4:7], v20, v92, v[4:7]
	v_lshlrev_b32_e32 v12, 16, v44
	v_mfma_f32_16x16x4_f32 v[8:11], v36, v93, v[8:11]
	v_and_b32_e32 v44, 0xffff0000, v44
	v_mfma_f32_16x16x4_f32 v[4:7], v21, v94, v[4:7]
	v_lshlrev_b32_e32 v13, 16, v45
	v_mfma_f32_16x16x4_f32 v[8:11], v37, v95, v[8:11]
	v_and_b32_e32 v45, 0xffff0000, v45
	v_mfma_f32_16x16x4_f32 v[4:7], v22, v96, v[4:7]
	v_lshlrev_b32_e32 v14, 16, v46
	v_mfma_f32_16x16x4_f32 v[8:11], v38, v97, v[8:11]
	v_and_b32_e32 v46, 0xffff0000, v46
	v_mfma_f32_16x16x4_f32 v[4:7], v23, v98, v[4:7]
	v_lshlrev_b32_e32 v15, 16, v47
	v_mfma_f32_16x16x4_f32 v[8:11], v39, v99, v[8:11]
	v_and_b32_e32 v47, 0xffff0000, v47
	v_mfma_f32_16x16x4_f32 v[4:7], v24, v100, v[4:7]
	v_lshlrev_b32_e32 v16, 16, v48
	v_mfma_f32_16x16x4_f32 v[8:11], v40, v101, v[8:11]
	v_and_b32_e32 v48, 0xffff0000, v48
	v_mfma_f32_16x16x4_f32 v[4:7], v25, v102, v[4:7]
	v_lshlrev_b32_e32 v17, 16, v49
	v_mfma_f32_16x16x4_f32 v[8:11], v41, v103, v[8:11]
	v_and_b32_e32 v49, 0xffff0000, v49
	v_mfma_f32_16x16x4_f32 v[4:7], v26, v104, v[4:7]
	v_lshlrev_b32_e32 v18, 16, v50
	v_mfma_f32_16x16x4_f32 v[8:11], v42, v105, v[8:11]
	v_and_b32_e32 v50, 0xffff0000, v50
	v_mfma_f32_16x16x4_f32 v[4:7], v27, v106, v[4:7]
	v_lshlrev_b32_e32 v19, 16, v51
	v_mfma_f32_16x16x4_f32 v[8:11], v43, v107, v[8:11]
	v_and_b32_e32 v51, 0xffff0000, v51
	global_load_dwordx4 v[36:39], v2, s[6:7] offset:1664
	global_load_dwordx4 v[40:43], v2, s[6:7] offset:1680
	global_load_dwordx4 v[92:95], v3, s[8:9] offset:2560
	global_load_dwordx4 v[96:99], v3, s[8:9] offset:2576
	global_load_dwordx4 v[100:103], v3, s[8:9] offset:2592
	global_load_dwordx4 v[104:107], v3, s[8:9] offset:2608
	s_waitcnt vmcnt(12)
; __global__ void __launch_bounds__(NWAVES * 64, 2) fwd_megakernel(Args args) {
;     ...
;                 for (int q = 0; q < 4; ++q) { float d = 0.f;
; #pragma unroll
;                     for (int jj = 0; jj < 4; ++jj) { const u32x4 w = pw[q][jj];
;                         d += __uint_as_float(w.x << 16) * wreg[8 * jj + 0] + __uint_as_float(w.x & 0xffff0000u) * wreg[8 * jj + 1] + __uint_as_float(w.y << 16) * wreg[8 * jj + 2] + __uint_as_float(w.y & 0xffff0000u) * wreg[8 * jj + 3]
;                            + __uint_as_float(w.z << 16) * wreg[8 * jj + 4] + __uint_as_float(w.z & 0xffff0000u) * wreg[8 * jj + 5] + __uint_as_float(w.w << 16) * wreg[8 * jj + 6] + __uint_as_float(w.w & 0xffff0000u) * wreg[8 * jj + 7]; }
	v_mfma_f32_16x16x4_f32 v[4:7], v12, v108, v[4:7]
	v_lshlrev_b32_e32 v20, 16, v52
	v_mfma_f32_16x16x4_f32 v[8:11], v44, v109, v[8:11]
	v_and_b32_e32 v52, 0xffff0000, v52
	v_mfma_f32_16x16x4_f32 v[4:7], v13, v110, v[4:7]
	v_lshlrev_b32_e32 v21, 16, v53
	v_mfma_f32_16x16x4_f32 v[8:11], v45, v111, v[8:11]
	v_and_b32_e32 v53, 0xffff0000, v53
	v_mfma_f32_16x16x4_f32 v[4:7], v14, v112, v[4:7]
	v_lshlrev_b32_e32 v22, 16, v54
	v_mfma_f32_16x16x4_f32 v[8:11], v46, v113, v[8:11]
	v_and_b32_e32 v54, 0xffff0000, v54
	v_mfma_f32_16x16x4_f32 v[4:7], v15, v114, v[4:7]
	v_lshlrev_b32_e32 v23, 16, v55
	v_mfma_f32_16x16x4_f32 v[8:11], v47, v115, v[8:11]
	v_and_b32_e32 v55, 0xffff0000, v55
	v_mfma_f32_16x16x4_f32 v[4:7], v16, v116, v[4:7]
	v_lshlrev_b32_e32 v24, 16, v56
	v_mfma_f32_16x16x4_f32 v[8:11], v48, v117, v[8:11]
	v_and_b32_e32 v56, 0xffff0000, v56
	v_mfma_f32_16x16x4_f32 v[4:7], v17, v118, v[4:7]
	v_lshlrev_b32_e32 v25, 16, v57
	v_mfma_f32_16x16x4_f32 v[8:11], v49, v119, v[8:11]
	v_and_b32_e32 v57, 0xffff0000, v57
	v_mfma_f32_16x16x4_f32 v[4:7], v18, v120, v[4:7]
	v_lshlrev_b32_e32 v26, 16, v58
	v_mfma_f32_16x16x4_f32 v[8:11], v50, v121, v[8:11]
	v_and_b32_e32 v58, 0xffff0000, v58
	v_mfma_f32_16x16x4_f32 v[4:7], v19, v122, v[4:7]
	v_lshlrev_b32_e32 v27, 16, v59
	v_mfma_f32_16x16x4_f32 v[8:11], v51, v123, v[8:11]
	v_and_b32_e32 v59, 0xffff0000, v59
	global_load_dwordx4 v[44:47], v2, s[6:7] offset:1792
	global_load_dwordx4 v[48:51], v2, s[6:7] offset:1808
	global_load_dwordx4 v[108:111], v3, s[8:9] offset:2816
	global_load_dwordx4 v[112:115], v3, s[8:9] offset:2832
	global_load_dwordx4 v[116:119], v3, s[8:9] offset:2848
	global_load_dwordx4 v[120:123], v3, s[8:9] offset:2864
	s_waitcnt vmcnt(12)
	v_mfma_f32_16x16x4_f32 v[4:7], v20, v76, v[4:7]
	v_lshlrev_b32_e32 v12, 16, v60
	v_mfma_f32_16x16x4_f32 v[8:11], v52, v77, v[8:11]
	v_and_b32_e32 v60, 0xffff0000, v60
	v_mfma_f32_16x16x4_f32 v[4:7], v21, v78, v[4:7]
	v_lshlrev_b32_e32 v13, 16, v61
	v_mfma_f32_16x16x4_f32 v[8:11], v53, v79, v[8:11]
	v_and_b32_e32 v61, 0xffff0000, v61
	v_mfma_f32_16x16x4_f32 v[4:7], v22, v80, v[4:7]
	v_lshlrev_b32_e32 v14, 16, v62
	v_mfma_f32_16x16x4_f32 v[8:11], v54, v81, v[8:11]
	v_and_b32_e32 v62, 0xffff0000, v62
	v_mfma_f32_16x16x4_f32 v[4:7], v23, v82, v[4:7]
	v_lshlrev_b32_e32 v15, 16, v63
	v_mfma_f32_16x16x4_f32 v[8:11], v55, v83, v[8:11]
	v_and_b32_e32 v63, 0xffff0000, v63
	v_mfma_f32_16x16x4_f32 v[4:7], v24, v84, v[4:7]
	v_lshlrev_b32_e32 v16, 16, v64
	v_mfma_f32_16x16x4_f32 v[8:11], v56, v85, v[8:11]
	v_and_b32_e32 v64, 0xffff0000, v64
	v_mfma_f32_16x16x4_f32 v[4:7], v25, v86, v[4:7]
	v_lshlrev_b32_e32 v17, 16, v65
	v_mfma_f32_16x16x4_f32 v[8:11], v57, v87, v[8:11]
	v_and_b32_e32 v65, 0xffff0000, v65
	v_mfma_f32_16x16x4_f32 v[4:7], v26, v88, v[4:7]
	v_lshlrev_b32_e32 v18, 16, v66
	v_mfma_f32_16x16x4_f32 v[8:11], v58, v89, v[8:11]
	v_and_b32_e32 v66, 0xffff0000, v66
	v_mfma_f32_16x16x4_f32 v[4:7], v27, v90, v[4:7]
	v_lshlrev_b32_e32 v19, 16, v67
	v_mfma_f32_16x16x4_f32 v[8:11], v59, v91, v[8:11]
	v_and_b32_e32 v67, 0xffff0000, v67
	global_load_dwordx4 v[52:55], v2, s[6:7] offset:1920
	global_load_dwordx4 v[56:59], v2, s[6:7] offset:1936
	global_load_dwordx4 v[76:79], v3, s[8:9] offset:3072
	global_load_dwordx4 v[80:83], v3, s[8:9] offset:3088
	global_load_dwordx4 v[84:87], v3, s[8:9] offset:3104
	global_load_dwordx4 v[88:91], v3, s[8:9] offset:3120
	s_waitcnt vmcnt(12)
	v_mfma_f32_16x16x4_f32 v[4:7], v12, v92, v[4:7]
	v_lshlrev_b32_e32 v20, 16, v68
	v_mfma_f32_16x16x4_f32 v[8:11], v60, v93, v[8:11]
	v_and_b32_e32 v68, 0xffff0000, v68
	v_mfma_f32_16x16x4_f32 v[4:7], v13, v94, v[4:7]
	v_lshlrev_b32_e32 v21, 16, v69
	v_mfma_f32_16x16x4_f32 v[8:11], v61, v95, v[8:11]
	v_and_b32_e32 v69, 0xffff0000, v69
	v_mfma_f32_16x16x4_f32 v[4:7], v14, v96, v[4:7]
	v_lshlrev_b32_e32 v22, 16, v70
	v_mfma_f32_16x16x4_f32 v[8:11], v62, v97, v[8:11]
	v_and_b32_e32 v70, 0xffff0000, v70
	v_mfma_f32_16x16x4_f32 v[4:7], v15, v98, v[4:7]
	v_lshlrev_b32_e32 v23, 16, v71
	v_mfma_f32_16x16x4_f32 v[8:11], v63, v99, v[8:11]
	v_and_b32_e32 v71, 0xffff0000, v71
	v_mfma_f32_16x16x4_f32 v[4:7], v16, v100, v[4:7]
	v_lshlrev_b32_e32 v24, 16, v72
	v_mfma_f32_16x16x4_f32 v[8:11], v64, v101, v[8:11]
	v_and_b32_e32 v72, 0xffff0000, v72
	v_mfma_f32_16x16x4_f32 v[4:7], v17, v102, v[4:7]
	v_lshlrev_b32_e32 v25, 16, v73
	v_mfma_f32_16x16x4_f32 v[8:11], v65, v103, v[8:11]
	v_and_b32_e32 v73, 0xffff0000, v73
	v_mfma_f32_16x16x4_f32 v[4:7], v18, v104, v[4:7]
	v_lshlrev_b32_e32 v26, 16, v74
	v_mfma_f32_16x16x4_f32 v[8:11], v66, v105, v[8:11]
	v_and_b32_e32 v74, 0xffff0000, v74
	v_mfma_f32_16x16x4_f32 v[4:7], v19, v106, v[4:7]
	v_lshlrev_b32_e32 v27, 16, v75
	v_mfma_f32_16x16x4_f32 v[8:11], v67, v107, v[8:11]
	v_and_b32_e32 v75, 0xffff0000, v75
	global_load_dwordx4 v[92:95], v3, s[8:9] offset:3328
	global_load_dwordx4 v[96:99], v3, s[8:9] offset:3344
	global_load_dwordx4 v[100:103], v3, s[8:9] offset:3360
	global_load_dwordx4 v[104:107], v3, s[8:9] offset:3376
	s_waitcnt vmcnt(10)
; __global__ void __launch_bounds__(NWAVES * 64, 2) fwd_megakernel(Args args) {
;     ...
;                 for (int q = 0; q < 4; ++q) { float d = 0.f;
; #pragma unroll
;                     for (int jj = 0; jj < 4; ++jj) { const u32x4 w = pw[q][jj];
;                         d += __uint_as_float(w.x << 16) * wreg[8 * jj + 0] + __uint_as_float(w.x & 0xffff0000u) * wreg[8 * jj + 1] + __uint_as_float(w.y << 16) * wreg[8 * jj + 2] + __uint_as_float(w.y & 0xffff0000u) * wreg[8 * jj + 3]
;                            + __uint_as_float(w.z << 16) * wreg[8 * jj + 4] + __uint_as_float(w.z & 0xffff0000u) * wreg[8 * jj + 5] + __uint_as_float(w.w << 16) * wreg[8 * jj + 6] + __uint_as_float(w.w & 0xffff0000u) * wreg[8 * jj + 7]; }
	v_mfma_f32_16x16x4_f32 v[4:7], v20, v108, v[4:7]
	v_lshlrev_b32_e32 v12, 16, v28
	v_mfma_f32_16x16x4_f32 v[8:11], v68, v109, v[8:11]
	v_and_b32_e32 v28, 0xffff0000, v28
	v_mfma_f32_16x16x4_f32 v[4:7], v21, v110, v[4:7]
	v_lshlrev_b32_e32 v13, 16, v29
	v_mfma_f32_16x16x4_f32 v[8:11], v69, v111, v[8:11]
	v_and_b32_e32 v29, 0xffff0000, v29
	v_mfma_f32_16x16x4_f32 v[4:7], v22, v112, v[4:7]
	v_lshlrev_b32_e32 v14, 16, v30
	v_mfma_f32_16x16x4_f32 v[8:11], v70, v113, v[8:11]
	v_and_b32_e32 v30, 0xffff0000, v30
	v_mfma_f32_16x16x4_f32 v[4:7], v23, v114, v[4:7]
	v_lshlrev_b32_e32 v15, 16, v31
	v_mfma_f32_16x16x4_f32 v[8:11], v71, v115, v[8:11]
	v_and_b32_e32 v31, 0xffff0000, v31
	v_mfma_f32_16x16x4_f32 v[4:7], v24, v116, v[4:7]
	v_lshlrev_b32_e32 v16, 16, v32
	v_mfma_f32_16x16x4_f32 v[8:11], v72, v117, v[8:11]
	v_and_b32_e32 v32, 0xffff0000, v32
	v_mfma_f32_16x16x4_f32 v[4:7], v25, v118, v[4:7]
	v_lshlrev_b32_e32 v17, 16, v33
	v_mfma_f32_16x16x4_f32 v[8:11], v73, v119, v[8:11]
	v_and_b32_e32 v33, 0xffff0000, v33
	v_mfma_f32_16x16x4_f32 v[4:7], v26, v120, v[4:7]
	v_lshlrev_b32_e32 v18, 16, v34
	v_mfma_f32_16x16x4_f32 v[8:11], v74, v121, v[8:11]
	v_and_b32_e32 v34, 0xffff0000, v34
	v_mfma_f32_16x16x4_f32 v[4:7], v27, v122, v[4:7]
	v_lshlrev_b32_e32 v19, 16, v35
	v_mfma_f32_16x16x4_f32 v[8:11], v75, v123, v[8:11]
	v_and_b32_e32 v35, 0xffff0000, v35
	global_load_dwordx4 v[108:111], v3, s[8:9] offset:3584
	global_load_dwordx4 v[112:115], v3, s[8:9] offset:3600
	global_load_dwordx4 v[116:119], v3, s[8:9] offset:3616
	global_load_dwordx4 v[120:123], v3, s[8:9] offset:3632
	s_waitcnt vmcnt(8)
	v_mfma_f32_16x16x4_f32 v[4:7], v12, v76, v[4:7]
	v_lshlrev_b32_e32 v20, 16, v36
	v_mfma_f32_16x16x4_f32 v[8:11], v28, v77, v[8:11]
	v_and_b32_e32 v36, 0xffff0000, v36
	v_mfma_f32_16x16x4_f32 v[4:7], v13, v78, v[4:7]
	v_lshlrev_b32_e32 v21, 16, v37
	v_mfma_f32_16x16x4_f32 v[8:11], v29, v79, v[8:11]
	v_and_b32_e32 v37, 0xffff0000, v37
	v_mfma_f32_16x16x4_f32 v[4:7], v14, v80, v[4:7]
	v_lshlrev_b32_e32 v22, 16, v38
	v_mfma_f32_16x16x4_f32 v[8:11], v30, v81, v[8:11]
	v_and_b32_e32 v38, 0xffff0000, v38
	v_mfma_f32_16x16x4_f32 v[4:7], v15, v82, v[4:7]
	v_lshlrev_b32_e32 v23, 16, v39
	v_mfma_f32_16x16x4_f32 v[8:11], v31, v83, v[8:11]
	v_and_b32_e32 v39, 0xffff0000, v39
	v_mfma_f32_16x16x4_f32 v[4:7], v16, v84, v[4:7]
	v_lshlrev_b32_e32 v24, 16, v40
	v_mfma_f32_16x16x4_f32 v[8:11], v32, v85, v[8:11]
	v_and_b32_e32 v40, 0xffff0000, v40
	v_mfma_f32_16x16x4_f32 v[4:7], v17, v86, v[4:7]
	v_lshlrev_b32_e32 v25, 16, v41
	v_mfma_f32_16x16x4_f32 v[8:11], v33, v87, v[8:11]
	v_and_b32_e32 v41, 0xffff0000, v41
	v_mfma_f32_16x16x4_f32 v[4:7], v18, v88, v[4:7]
	v_lshlrev_b32_e32 v26, 16, v42
	v_mfma_f32_16x16x4_f32 v[8:11], v34, v89, v[8:11]
	v_and_b32_e32 v42, 0xffff0000, v42
	v_mfma_f32_16x16x4_f32 v[4:7], v19, v90, v[4:7]
	v_lshlrev_b32_e32 v27, 16, v43
	v_mfma_f32_16x16x4_f32 v[8:11], v35, v91, v[8:11]
	v_and_b32_e32 v43, 0xffff0000, v43
	global_load_dwordx4 v[76:79], v3, s[8:9] offset:3840
	global_load_dwordx4 v[80:83], v3, s[8:9] offset:3856
	global_load_dwordx4 v[84:87], v3, s[8:9] offset:3872
	global_load_dwordx4 v[88:91], v3, s[8:9] offset:3888
	s_waitcnt vmcnt(8)
	v_mfma_f32_16x16x4_f32 v[4:7], v20, v92, v[4:7]
	v_lshlrev_b32_e32 v12, 16, v44
	v_mfma_f32_16x16x4_f32 v[8:11], v36, v93, v[8:11]
	v_and_b32_e32 v44, 0xffff0000, v44
	v_mfma_f32_16x16x4_f32 v[4:7], v21, v94, v[4:7]
	v_lshlrev_b32_e32 v13, 16, v45
	v_mfma_f32_16x16x4_f32 v[8:11], v37, v95, v[8:11]
	v_and_b32_e32 v45, 0xffff0000, v45
	v_mfma_f32_16x16x4_f32 v[4:7], v22, v96, v[4:7]
	v_lshlrev_b32_e32 v14, 16, v46
	v_mfma_f32_16x16x4_f32 v[8:11], v38, v97, v[8:11]
	v_and_b32_e32 v46, 0xffff0000, v46
	v_mfma_f32_16x16x4_f32 v[4:7], v23, v98, v[4:7]
	v_lshlrev_b32_e32 v15, 16, v47
	v_mfma_f32_16x16x4_f32 v[8:11], v39, v99, v[8:11]
	v_and_b32_e32 v47, 0xffff0000, v47
	v_mfma_f32_16x16x4_f32 v[4:7], v24, v100, v[4:7]
	v_lshlrev_b32_e32 v16, 16, v48
	v_mfma_f32_16x16x4_f32 v[8:11], v40, v101, v[8:11]
	v_and_b32_e32 v48, 0xffff0000, v48
	v_mfma_f32_16x16x4_f32 v[4:7], v25, v102, v[4:7]
	v_lshlrev_b32_e32 v17, 16, v49
	v_mfma_f32_16x16x4_f32 v[8:11], v41, v103, v[8:11]
	v_and_b32_e32 v49, 0xffff0000, v49
	v_mfma_f32_16x16x4_f32 v[4:7], v26, v104, v[4:7]
	v_lshlrev_b32_e32 v18, 16, v50
	v_mfma_f32_16x16x4_f32 v[8:11], v42, v105, v[8:11]
	v_and_b32_e32 v50, 0xffff0000, v50
	v_mfma_f32_16x16x4_f32 v[4:7], v27, v106, v[4:7]
	v_lshlrev_b32_e32 v19, 16, v51
	v_mfma_f32_16x16x4_f32 v[8:11], v43, v107, v[8:11]
	v_and_b32_e32 v51, 0xffff0000, v51
	s_waitcnt vmcnt(4)
; __device__ __forceinline__ float rs_from_ss(float ss) { return rsqrtf(ss * (1.0f / DM) + RMS_EPS); }
; __global__ void __launch_bounds__(NWAVES * 64, 2) fwd_megakernel(Args args) {
;     ...
;                 for (int q = 0; q < 4; ++q) { float d = 0.f;
; #pragma unroll
;                     for (int jj = 0; jj < 4; ++jj) { const u32x4 w = pw[q][jj];
;                         d += __uint_as_float(w.x << 16) * wreg[8 * jj + 0] + __uint_as_float(w.x & 0xffff0000u) * wreg[8 * jj + 1] + __uint_as_float(w.y << 16) * wreg[8 * jj + 2] + __uint_as_float(w.y & 0xffff0000u) * wreg[8 * jj + 3]
;                            + __uint_as_float(w.z << 16) * wreg[8 * jj + 4] + __uint_as_float(w.z & 0xffff0000u) * wreg[8 * jj + 5] + __uint_as_float(w.w << 16) * wreg[8 * jj + 6] + __uint_as_float(w.w & 0xffff0000u) * wreg[8 * jj + 7]; }
;                     d = wave_sum(d);
;                     if (ln == 0) { const int m = m0 + q; const float f = d * rs_from_ss(sq[q]) + bf; const float lf = fminf(f, 0.f) - log1pf(__expf(-fabsf(f)));
;                         logfb[((size_t)(m / SEQ) * NH + wave) * SEQ + (m % SEQ)] = lf; } }
	v_mfma_f32_16x16x4_f32 v[4:7], v12, v108, v[4:7]
	v_lshlrev_b32_e32 v20, 16, v52
	v_mfma_f32_16x16x4_f32 v[8:11], v44, v109, v[8:11]
	v_and_b32_e32 v52, 0xffff0000, v52
	v_mfma_f32_16x16x4_f32 v[4:7], v13, v110, v[4:7]
	v_lshlrev_b32_e32 v21, 16, v53
	v_mfma_f32_16x16x4_f32 v[8:11], v45, v111, v[8:11]
	v_and_b32_e32 v53, 0xffff0000, v53
	v_mfma_f32_16x16x4_f32 v[4:7], v14, v112, v[4:7]
	v_lshlrev_b32_e32 v22, 16, v54
	v_mfma_f32_16x16x4_f32 v[8:11], v46, v113, v[8:11]
	v_and_b32_e32 v54, 0xffff0000, v54
	v_mfma_f32_16x16x4_f32 v[4:7], v15, v114, v[4:7]
	v_lshlrev_b32_e32 v23, 16, v55
	v_mfma_f32_16x16x4_f32 v[8:11], v47, v115, v[8:11]
	v_and_b32_e32 v55, 0xffff0000, v55
	v_mfma_f32_16x16x4_f32 v[4:7], v16, v116, v[4:7]
	v_lshlrev_b32_e32 v24, 16, v56
	v_mfma_f32_16x16x4_f32 v[8:11], v48, v117, v[8:11]
	v_and_b32_e32 v56, 0xffff0000, v56
	v_mfma_f32_16x16x4_f32 v[4:7], v17, v118, v[4:7]
	v_lshlrev_b32_e32 v25, 16, v57
	v_mfma_f32_16x16x4_f32 v[8:11], v49, v119, v[8:11]
	v_and_b32_e32 v57, 0xffff0000, v57
	v_mfma_f32_16x16x4_f32 v[4:7], v18, v120, v[4:7]
	v_lshlrev_b32_e32 v26, 16, v58
	v_mfma_f32_16x16x4_f32 v[8:11], v50, v121, v[8:11]
	v_and_b32_e32 v58, 0xffff0000, v58
	v_mfma_f32_16x16x4_f32 v[4:7], v19, v122, v[4:7]
	v_lshlrev_b32_e32 v27, 16, v59
	v_mfma_f32_16x16x4_f32 v[8:11], v51, v123, v[8:11]
	v_and_b32_e32 v59, 0xffff0000, v59
	s_waitcnt vmcnt(0)
	v_mfma_f32_16x16x4_f32 v[4:7], v20, v76, v[4:7]
	v_mfma_f32_16x16x4_f32 v[8:11], v52, v77, v[8:11]
	v_mfma_f32_16x16x4_f32 v[4:7], v21, v78, v[4:7]
	v_mfma_f32_16x16x4_f32 v[8:11], v53, v79, v[8:11]
	v_mfma_f32_16x16x4_f32 v[4:7], v22, v80, v[4:7]
	v_mfma_f32_16x16x4_f32 v[8:11], v54, v81, v[8:11]
	v_mfma_f32_16x16x4_f32 v[4:7], v23, v82, v[4:7]
	v_mfma_f32_16x16x4_f32 v[8:11], v55, v83, v[8:11]
	v_mfma_f32_16x16x4_f32 v[4:7], v24, v84, v[4:7]
	v_mfma_f32_16x16x4_f32 v[8:11], v56, v85, v[8:11]
	v_mfma_f32_16x16x4_f32 v[4:7], v25, v86, v[4:7]
	v_mfma_f32_16x16x4_f32 v[8:11], v57, v87, v[8:11]
	v_mfma_f32_16x16x4_f32 v[4:7], v26, v88, v[4:7]
	v_mfma_f32_16x16x4_f32 v[8:11], v58, v89, v[8:11]
	v_mfma_f32_16x16x4_f32 v[4:7], v27, v90, v[4:7]
	v_mfma_f32_16x16x4_f32 v[8:11], v59, v91, v[8:11]
	v_lshrrev_b32_e32 v12, 3, v166
	v_and_b32_e32 v13, 7, v166
	v_lshlrev_b32_e32 v14, 2, v12
	v_lshlrev_b32_e32 v15, 2, v13
	s_lshl_b32 s5, s4, 2
	s_add_u32 s5, s5, 0x10000
	s_add_u32 s10, s60, s5
	s_addc_u32 s11, s61, 0
	global_load_dword v16, v14, s[10:11]
	global_load_dword v17, v15, s[16:17]
	s_nop 7
	v_add_f32_e32 v4, v4, v8
	v_add_f32_e32 v5, v5, v9
	v_add_f32_e32 v6, v6, v10
	v_add_f32_e32 v7, v7, v11
	v_and_b32_e32 v0, 15, v168
	v_lshrrev_b32_e32 v18, 4, v168
	v_lshlrev_b32_e32 v0, 2, v0
	v_lshl_or_b32 v0, v18, 8, v0
	s_lshl_b32 s5, s14, 12
	s_lshl_b32 s1, s13, 10
	s_add_u32 s5, s5, s1
	s_add_u32 s5, s5, 0x21000
	v_add_u32_e32 v0, s5, v0
	ds_write_b32 v0, v4 offset:0
	ds_write_b32 v0, v5 offset:64
	ds_write_b32 v0, v6 offset:128
	ds_write_b32 v0, v7 offset:192
	s_waitcnt lgkmcnt(0)
	s_barrier
	v_lshlrev_b32_e32 v18, 6, v12
	v_add_u32_e32 v18, v18, v15
	v_add_u32_e32 v18, 0x21000, v18
	ds_read_b32 v19, v18
	ds_read_b32 v20, v18 offset:4096
	s_lshr_b32 s5, s4, 11
	s_lshl_b32 s5, s5, 16
	s_and_b32 s1, s4, 0x7ff
	s_lshl_b32 s1, s1, 2
	s_add_u32 s5, s5, s1
	s_add_u32 s5, s5, 0x80000
	s_add_u32 s10, s60, s5
	s_addc_u32 s11, s61, 0
	v_lshl_or_b32 v21, v13, 13, v14
	s_waitcnt vmcnt(0) lgkmcnt(0)
	v_add_f32_e32 v19, v19, v20
	v_fmamk_f32 v16, v16, 0x3a000000, v172
	v_rsq_f32_e32 v16, v16
	s_nop 0
	v_fma_f32 v22, v19, v16, v17
	v_mul_f32_e64 v23, |v22|, s18
	v_exp_f32_e32 v23, v23
	s_nop 0
	v_add_f32_e32 v24, 1.0, v23
	v_add_f32_e32 v25, -1.0, v24
	v_sub_f32_e32 v25, v25, v23
	v_log_f32_e32 v26, v24
	v_rcp_f32_e32 v27, v24
	v_mov_b32_e32 v28, 0x3eaaaaab
	v_fmac_f32_e32 v28, 0xbe800000, v23
	v_mul_f32_e32 v26, s19, v26
	v_fma_f32 v26, -v25, v27, v26
	v_fma_f32 v28, v23, v28, -0.5
	v_fma_f32 v28, v23, v28, 1.0
	v_mul_f32_e32 v28, v23, v28
	v_cmp_gt_f32_e32 vcc, 0x3c800000, v23
	v_min_f32_e32 v29, 0, v22
	s_nop 0
	v_cndmask_b32_e32 v26, v26, v28, vcc
	v_sub_f32_e32 v29, v29, v26
	global_store_dword v21, v29, s[10:11]
	s_lshl_b32 s5, s21, 4
	s_add_i32 s4, s4, s5
	s_cmpk_gt_i32 s4, 0x3fff
	s_cbranch_scc1 .Llg_done
	s_barrier
	s_branch .Llg_trip
.Llg_done:
	s_branch .LBB0_608
.LBB0_605:
	s_mov_b64 s[4:5], 0
	s_mov_b64 s[6:7], 0
	s_and_b64 vcc, exec, s[8:9]
	s_cbranch_vccnz .LBB0_609
	s_branch .LBB0_613

; #define PG8_STAGE(bufoff, gbase, voff) do { _Pragma("unroll") for (int _i = 0; _i < 2; ++_i) \
;         __builtin_amdgcn_global_load_lds((const unsigned*)((const char*)(gbase) + (voff)[_i]), (LAS unsigned*)(lds + (bufoff) + ldsw + _i * 8192), 16, 0, 0); } while (0)
; #define PG8_LDA(dst, b, h) do { _Pragma("unroll") for (int m = 0; m < 4; ++m) _Pragma("unroll") for (int k = 0; k < 2; ++k) dst[m][k] = *(const LAS bf16x8*)(lds + PG8_SA(b, h) + aoff + m * 2048 + k * 1024); } while (0)
; #define PG8_LDB(dst, b, h) do { _Pragma("unroll") for (int n = 0; n < 2; ++n) _Pragma("unroll") for (int k = 0; k < 2; ++k) dst[n][k] = *(const LAS bf16x8*)(lds + PG8_SB(b, h) + boff + n * 2048 + k * 1024); } while (0)
; #define PG8_MMA(ai, bj, At, Bt) do { __builtin_amdgcn_s_setprio(1); _Pragma("unroll") for (int m = 0; m < 4; ++m) _Pragma("unroll") for (int n = 0; n < 2; ++n) _Pragma("unroll") for (int k = 0; k < 2; ++k) \
;         acc[ai][bj][m][n] = __builtin_amdgcn_mfma_f32_16x16x32_bf16(Bt[n][k], At[m][k], acc[ai][bj][m][n], 0, 0, 0); __builtin_amdgcn_s_setprio(0); } while (0)
; #define PG8_WAIT_V(n) asm volatile("s_waitcnt vmcnt(" #n ")" ::: "memory")
; #define PG8_WAIT_L(n) asm volatile("s_waitcnt lgkmcnt(" #n ")" ::: "memory")
; #define PG8_BAR __builtin_amdgcn_s_barrier()
; #define PG8_SCHED __builtin_amdgcn_sched_barrier(0)
; __device__ __forceinline__ void gemm_phase(LAS unsigned char* lds, const Gemm g, const StaticOrder& S, const Epi& E) {
;     ...
;             const char* a1 = cA + (size_t)(t + 1) * kstep;
;             const char* a2 = last ? nA : cA + (size_t)(t + 2) * kstep; const char* b2 = last ? nB : cB + (size_t)(t + 2) * kstep;
;             const char* a3 = a2 + kstep; const char* b3 = b2 + kstep;
;             PG8_LDB(B0, 0, 0); PG8_LDB(B1, 0, 1); PG8_SCHED; PG8_LDA(At, 0, 0); PG8_STAGE(PG8_SA(1, 1), a1 + hstep, voffA);
;             PG8_WAIT_V(8); PG8_WAIT_L(0); PG8_BAR; PG8_MMA(0, 0, At, B0); PG8_MMA(0, 1, At, B1); PG8_BAR; PG8_SCHED;
;             PG8_LDA(At, 0, 1); PG8_STAGE(PG8_SB(0, 0), b2, voffB); PG8_STAGE(PG8_SB(0, 1), b2 + hstep, voffB); PG8_STAGE(PG8_SA(0, 0), a2, voffA);
;             PG8_WAIT_V(8); PG8_WAIT_L(0); PG8_BAR; PG8_MMA(1, 0, At, B0); PG8_MMA(1, 1, At, B1); PG8_BAR; PG8_SCHED;
.LBB0_662:
	s_add_i32 s42, s22, 2
	s_add_u32 s10, s40, 0x80
	s_addc_u32 s11, s41, 0
	s_add_i32 s43, 0, 0x10000
	s_cmp_eq_u32 s73, s22
	s_cselect_b32 s23, s19, s11
	s_cselect_b32 s22, s18, s10
	s_cselect_b32 s99, s21, s25
	s_cselect_b32 s98, s20, s24
	s_add_i32 s47, 0, 0x14000
	v_add_u32_e32 v142, s43, v215
	v_add_u32_e32 v158, s47, v215
	ds_read_b128 v[130:133], v142
	ds_read_b128 v[134:137], v142 offset:1024
	ds_read_b128 v[138:141], v142 offset:2048
	ds_read_b128 v[142:145], v142 offset:3072
	ds_read_b128 v[146:149], v158
	ds_read_b128 v[150:153], v158 offset:1024
	ds_read_b128 v[154:157], v158 offset:2048
	ds_read_b128 v[158:161], v158 offset:3072
	s_add_i32 m0, s77, 0xc000
	ds_read_b128 v[162:165], v221
	ds_read_b128 v[188:191], v221 offset:1024
	ds_read_b128 v[192:195], v221 offset:2048
	ds_read_b128 v[196:199], v221 offset:3072
	ds_read_b128 v[200:203], v221 offset:4096
	ds_read_b128 v[222:225], v221 offset:5120
	ds_read_b128 v[226:229], v221 offset:6144
	ds_read_b128 v[230:233], v221 offset:7168
	global_load_lds_dwordx4 v184, s[40:41]
	s_add_i32 m0, s77, 0xe000
	s_add_u32 s100, s98, s64
	s_addc_u32 s101, s99, 0
	global_load_lds_dwordx4 v186, s[40:41]
	s_waitcnt vmcnt(8)
	s_waitcnt lgkmcnt(0)
	s_barrier
	s_setprio 1
	s_waitcnt lgkmcnt(0)
	v_mfma_f32_16x16x32_bf16 v[126:129], v[130:133], v[162:165], v[126:129]
	v_mfma_f32_16x16x32_bf16 v[118:121], v[138:141], v[162:165], v[118:121]
	v_mfma_f32_16x16x32_bf16 v[110:113], v[130:133], v[192:195], v[110:113]
	v_mfma_f32_16x16x32_bf16 v[102:105], v[138:141], v[192:195], v[102:105]
	v_mfma_f32_16x16x32_bf16 v[94:97], v[130:133], v[200:203], v[94:97]
	v_mfma_f32_16x16x32_bf16 v[86:89], v[138:141], v[200:203], v[86:89]
	v_mfma_f32_16x16x32_bf16 v[78:81], v[130:133], v[226:229], v[78:81]
	v_mfma_f32_16x16x32_bf16 v[70:73], v[138:141], v[226:229], v[70:73]
	v_mfma_f32_16x16x32_bf16 v[126:129], v[134:137], v[188:191], v[126:129]
	v_mfma_f32_16x16x32_bf16 v[118:121], v[142:145], v[188:191], v[118:121]
	v_mfma_f32_16x16x32_bf16 v[110:113], v[134:137], v[196:199], v[110:113]
	v_mfma_f32_16x16x32_bf16 v[102:105], v[142:145], v[196:199], v[102:105]
	v_mfma_f32_16x16x32_bf16 v[94:97], v[134:137], v[222:225], v[94:97]
	v_mfma_f32_16x16x32_bf16 v[86:89], v[142:145], v[222:225], v[86:89]
	v_mfma_f32_16x16x32_bf16 v[78:81], v[134:137], v[230:233], v[78:81]
	v_mfma_f32_16x16x32_bf16 v[70:73], v[142:145], v[230:233], v[70:73]
	s_setprio 0
	s_setprio 1
	v_mfma_f32_16x16x32_bf16 v[122:125], v[146:149], v[162:165], v[122:125]
	v_mfma_f32_16x16x32_bf16 v[114:117], v[154:157], v[162:165], v[114:117]
	v_mfma_f32_16x16x32_bf16 v[106:109], v[146:149], v[192:195], v[106:109]
	v_mfma_f32_16x16x32_bf16 v[98:101], v[154:157], v[192:195], v[98:101]
	v_mfma_f32_16x16x32_bf16 v[90:93], v[146:149], v[200:203], v[90:93]
	v_mfma_f32_16x16x32_bf16 v[82:85], v[154:157], v[200:203], v[82:85]
	v_mfma_f32_16x16x32_bf16 v[74:77], v[146:149], v[226:229], v[74:77]
	v_mfma_f32_16x16x32_bf16 v[66:69], v[154:157], v[226:229], v[66:69]
	v_mfma_f32_16x16x32_bf16 v[122:125], v[150:153], v[188:191], v[122:125]
	v_mfma_f32_16x16x32_bf16 v[114:117], v[158:161], v[188:191], v[114:117]
	v_mfma_f32_16x16x32_bf16 v[106:109], v[150:153], v[196:199], v[106:109]
	v_mfma_f32_16x16x32_bf16 v[98:101], v[158:161], v[196:199], v[98:101]
	v_mfma_f32_16x16x32_bf16 v[90:93], v[150:153], v[222:225], v[90:93]
	v_mfma_f32_16x16x32_bf16 v[82:85], v[158:161], v[222:225], v[82:85]
	v_mfma_f32_16x16x32_bf16 v[74:77], v[150:153], v[230:233], v[74:77]
	v_mfma_f32_16x16x32_bf16 v[66:69], v[158:161], v[230:233], v[66:69]
	s_setprio 0
	s_barrier
	s_add_i32 s43, s43, s76
	s_mov_b32 m0, s43
	ds_read_b128 v[162:165], v221 offset:16384
	ds_read_b128 v[188:191], v221 offset:17408
	ds_read_b128 v[192:195], v221 offset:18432
	ds_read_b128 v[196:199], v221 offset:19456
	ds_read_b128 v[200:203], v221 offset:20480
	ds_read_b128 v[222:225], v221 offset:21504
	ds_read_b128 v[226:229], v221 offset:22528
	ds_read_b128 v[230:233], v221 offset:23552
	global_load_lds_dwordx4 v0, s[98:99]
	s_add_i32 m0, s43, 0x2000
	s_add_i32 s43, s47, s76
	global_load_lds_dwordx4 v180, s[98:99]
	s_mov_b32 m0, s43
	s_nop 0
	global_load_lds_dwordx4 v0, s[100:101]
	s_add_i32 m0, s43, 0x2000
	s_nop 0
	global_load_lds_dwordx4 v180, s[100:101]
	s_mov_b32 m0, s77
	s_nop 0
	global_load_lds_dwordx4 v176, s[22:23]
	s_mov_b32 m0, s88
	s_nop 0
	global_load_lds_dwordx4 v178, s[22:23]
	s_waitcnt vmcnt(8)
	s_waitcnt lgkmcnt(0)
	s_barrier
	s_setprio 1
	s_waitcnt lgkmcnt(0)
	v_mfma_f32_16x16x32_bf16 v[62:65], v[130:133], v[162:165], v[62:65]
	v_mfma_f32_16x16x32_bf16 v[54:57], v[138:141], v[162:165], v[54:57]
	v_mfma_f32_16x16x32_bf16 v[46:49], v[130:133], v[192:195], v[46:49]
	v_mfma_f32_16x16x32_bf16 v[38:41], v[138:141], v[192:195], v[38:41]
	v_mfma_f32_16x16x32_bf16 v[30:33], v[130:133], v[200:203], v[30:33]
	v_mfma_f32_16x16x32_bf16 v[22:25], v[138:141], v[200:203], v[22:25]
	v_mfma_f32_16x16x32_bf16 v[14:17], v[130:133], v[226:229], v[14:17]
	v_mfma_f32_16x16x32_bf16 v[6:9], v[138:141], v[226:229], v[6:9]
	v_mfma_f32_16x16x32_bf16 v[62:65], v[134:137], v[188:191], v[62:65]
	v_mfma_f32_16x16x32_bf16 v[54:57], v[142:145], v[188:191], v[54:57]
	v_mfma_f32_16x16x32_bf16 v[46:49], v[134:137], v[196:199], v[46:49]
	v_mfma_f32_16x16x32_bf16 v[38:41], v[142:145], v[196:199], v[38:41]
	v_mfma_f32_16x16x32_bf16 v[30:33], v[134:137], v[222:225], v[30:33]
	v_mfma_f32_16x16x32_bf16 v[22:25], v[142:145], v[222:225], v[22:25]
	v_mfma_f32_16x16x32_bf16 v[14:17], v[134:137], v[230:233], v[14:17]
	v_mfma_f32_16x16x32_bf16 v[6:9], v[142:145], v[230:233], v[6:9]
	s_setprio 0
	s_setprio 1
	v_mfma_f32_16x16x32_bf16 v[58:61], v[146:149], v[162:165], v[58:61]
	v_mfma_f32_16x16x32_bf16 v[50:53], v[154:157], v[162:165], v[50:53]
	v_mfma_f32_16x16x32_bf16 v[42:45], v[146:149], v[192:195], v[42:45]
	v_mfma_f32_16x16x32_bf16 v[34:37], v[154:157], v[192:195], v[34:37]
	v_mfma_f32_16x16x32_bf16 v[26:29], v[146:149], v[200:203], v[26:29]
	v_mfma_f32_16x16x32_bf16 v[18:21], v[154:157], v[200:203], v[18:21]
	v_mfma_f32_16x16x32_bf16 v[10:13], v[146:149], v[226:229], v[10:13]
	v_mfma_f32_16x16x32_bf16 v[2:5], v[154:157], v[226:229], v[2:5]
	v_mfma_f32_16x16x32_bf16 v[58:61], v[150:153], v[188:191], v[58:61]
	v_mfma_f32_16x16x32_bf16 v[50:53], v[158:161], v[188:191], v[50:53]
	v_mfma_f32_16x16x32_bf16 v[42:45], v[150:153], v[196:199], v[42:45]
	v_mfma_f32_16x16x32_bf16 v[34:37], v[158:161], v[196:199], v[34:37]
	v_mfma_f32_16x16x32_bf16 v[26:29], v[150:153], v[222:225], v[26:29]
	v_mfma_f32_16x16x32_bf16 v[18:21], v[158:161], v[222:225], v[18:21]
	v_mfma_f32_16x16x32_bf16 v[10:13], v[150:153], v[230:233], v[10:13]
	v_mfma_f32_16x16x32_bf16 v[2:5], v[158:161], v[230:233], v[2:5]
	s_setprio 0
	s_barrier
; #define PG8_STAGE(bufoff, gbase, voff) do { _Pragma("unroll") for (int _i = 0; _i < 2; ++_i) \
;         __builtin_amdgcn_global_load_lds((const unsigned*)((const char*)(gbase) + (voff)[_i]), (LAS unsigned*)(lds + (bufoff) + ldsw + _i * 8192), 16, 0, 0); } while (0)
; #define PG8_LDA(dst, b, h) do { _Pragma("unroll") for (int m = 0; m < 4; ++m) _Pragma("unroll") for (int k = 0; k < 2; ++k) dst[m][k] = *(const LAS bf16x8*)(lds + PG8_SA(b, h) + aoff + m * 2048 + k * 1024); } while (0)
; #define PG8_LDB(dst, b, h) do { _Pragma("unroll") for (int n = 0; n < 2; ++n) _Pragma("unroll") for (int k = 0; k < 2; ++k) dst[n][k] = *(const LAS bf16x8*)(lds + PG8_SB(b, h) + boff + n * 2048 + k * 1024); } while (0)
; #define PG8_MMA(ai, bj, At, Bt) do { __builtin_amdgcn_s_setprio(1); _Pragma("unroll") for (int m = 0; m < 4; ++m) _Pragma("unroll") for (int n = 0; n < 2; ++n) _Pragma("unroll") for (int k = 0; k < 2; ++k) \
;         acc[ai][bj][m][n] = __builtin_amdgcn_mfma_f32_16x16x32_bf16(Bt[n][k], At[m][k], acc[ai][bj][m][n], 0, 0, 0); __builtin_amdgcn_s_setprio(0); } while (0)
; #define PG8_WAIT_V(n) asm volatile("s_waitcnt vmcnt(" #n ")" ::: "memory")
; #define PG8_WAIT_L(n) asm volatile("s_waitcnt lgkmcnt(" #n ")" ::: "memory")
; #define PG8_BAR __builtin_amdgcn_s_barrier()
; #define PG8_SCHED __builtin_amdgcn_sched_barrier(0)
; __device__ __forceinline__ void gemm_phase(LAS unsigned char* lds, const Gemm g, const StaticOrder& S, const Epi& E) {
;     ...
;             PG8_LDB(B0, 1, 0); PG8_LDB(B1, 1, 1); PG8_SCHED; PG8_LDA(At, 1, 0); PG8_STAGE(PG8_SA(0, 1), a2 + hstep, voffA);
;             PG8_WAIT_V(8); PG8_WAIT_L(0); PG8_BAR; PG8_MMA(0, 0, At, B0); PG8_MMA(0, 1, At, B1); PG8_BAR; PG8_SCHED;
;             PG8_LDA(At, 1, 1); PG8_STAGE(PG8_SB(1, 0), b3, voffB); PG8_STAGE(PG8_SB(1, 1), b3 + hstep, voffB); PG8_STAGE(PG8_SA(1, 0), a3, voffA);
;             PG8_WAIT_V(8); PG8_WAIT_L(0); PG8_BAR; PG8_MMA(1, 0, At, B0); PG8_MMA(1, 1, At, B1); PG8_BAR; PG8_SCHED;
;         }
	s_add_i32 s43, 0, 0x1c000
	v_add_u32_e32 v142, s89, v215
	v_add_u32_e32 v158, s43, v215
	ds_read_b128 v[130:133], v142
	ds_read_b128 v[134:137], v142 offset:1024
	ds_read_b128 v[138:141], v142 offset:2048
	ds_read_b128 v[142:145], v142 offset:3072
	ds_read_b128 v[146:149], v158
	ds_read_b128 v[150:153], v158 offset:1024
	ds_read_b128 v[154:157], v158 offset:2048
	ds_read_b128 v[158:161], v158 offset:3072
	s_add_u32 s10, s22, s64
	s_addc_u32 s11, s23, 0
	s_mov_b32 m0, s26
	ds_read_b128 v[162:165], v221 offset:32768
	ds_read_b128 v[188:191], v221 offset:33792
	ds_read_b128 v[192:195], v221 offset:34816
	ds_read_b128 v[196:199], v221 offset:35840
	ds_read_b128 v[200:203], v221 offset:36864
	ds_read_b128 v[222:225], v221 offset:37888
	ds_read_b128 v[226:229], v221 offset:38912
	ds_read_b128 v[230:233], v221 offset:39936
	global_load_lds_dwordx4 v176, s[10:11]
	s_mov_b32 m0, s48
	s_nop 0
	global_load_lds_dwordx4 v178, s[10:11]
	s_waitcnt vmcnt(8)
	s_waitcnt lgkmcnt(0)
	s_barrier
	s_setprio 1
	s_waitcnt lgkmcnt(0)
	v_mfma_f32_16x16x32_bf16 v[126:129], v[130:133], v[162:165], v[126:129]
	v_mfma_f32_16x16x32_bf16 v[118:121], v[138:141], v[162:165], v[118:121]
	v_mfma_f32_16x16x32_bf16 v[110:113], v[130:133], v[192:195], v[110:113]
	v_mfma_f32_16x16x32_bf16 v[102:105], v[138:141], v[192:195], v[102:105]
	v_mfma_f32_16x16x32_bf16 v[94:97], v[130:133], v[200:203], v[94:97]
	v_mfma_f32_16x16x32_bf16 v[86:89], v[138:141], v[200:203], v[86:89]
	v_mfma_f32_16x16x32_bf16 v[78:81], v[130:133], v[226:229], v[78:81]
	v_mfma_f32_16x16x32_bf16 v[70:73], v[138:141], v[226:229], v[70:73]
	v_mfma_f32_16x16x32_bf16 v[126:129], v[134:137], v[188:191], v[126:129]
	v_mfma_f32_16x16x32_bf16 v[118:121], v[142:145], v[188:191], v[118:121]
	v_mfma_f32_16x16x32_bf16 v[110:113], v[134:137], v[196:199], v[110:113]
	v_mfma_f32_16x16x32_bf16 v[102:105], v[142:145], v[196:199], v[102:105]
	v_mfma_f32_16x16x32_bf16 v[94:97], v[134:137], v[222:225], v[94:97]
	v_mfma_f32_16x16x32_bf16 v[86:89], v[142:145], v[222:225], v[86:89]
	v_mfma_f32_16x16x32_bf16 v[78:81], v[134:137], v[230:233], v[78:81]
	v_mfma_f32_16x16x32_bf16 v[70:73], v[142:145], v[230:233], v[70:73]
	s_setprio 0
	s_setprio 1
	v_mfma_f32_16x16x32_bf16 v[122:125], v[146:149], v[162:165], v[122:125]
	v_mfma_f32_16x16x32_bf16 v[114:117], v[154:157], v[162:165], v[114:117]
	v_mfma_f32_16x16x32_bf16 v[106:109], v[146:149], v[192:195], v[106:109]
	v_mfma_f32_16x16x32_bf16 v[98:101], v[154:157], v[192:195], v[98:101]
	v_mfma_f32_16x16x32_bf16 v[90:93], v[146:149], v[200:203], v[90:93]
	v_mfma_f32_16x16x32_bf16 v[82:85], v[154:157], v[200:203], v[82:85]
	v_mfma_f32_16x16x32_bf16 v[74:77], v[146:149], v[226:229], v[74:77]
	v_mfma_f32_16x16x32_bf16 v[66:69], v[154:157], v[226:229], v[66:69]
	v_mfma_f32_16x16x32_bf16 v[122:125], v[150:153], v[188:191], v[122:125]
	v_mfma_f32_16x16x32_bf16 v[114:117], v[158:161], v[188:191], v[114:117]
	v_mfma_f32_16x16x32_bf16 v[106:109], v[150:153], v[196:199], v[106:109]
	v_mfma_f32_16x16x32_bf16 v[98:101], v[158:161], v[196:199], v[98:101]
	v_mfma_f32_16x16x32_bf16 v[90:93], v[150:153], v[222:225], v[90:93]
	v_mfma_f32_16x16x32_bf16 v[82:85], v[158:161], v[222:225], v[82:85]
	v_mfma_f32_16x16x32_bf16 v[74:77], v[150:153], v[230:233], v[74:77]
	v_mfma_f32_16x16x32_bf16 v[66:69], v[158:161], v[230:233], v[66:69]
	s_setprio 0
	s_barrier
	s_add_i32 m0, s89, s76
	s_add_u32 s10, s98, 0x80
	s_addc_u32 s11, s99, 0
	ds_read_b128 v[162:165], v221 offset:49152
	ds_read_b128 v[188:191], v221 offset:50176
	ds_read_b128 v[192:195], v221 offset:51200
	ds_read_b128 v[196:199], v221 offset:52224
	ds_read_b128 v[200:203], v221 offset:53248
	ds_read_b128 v[222:225], v221 offset:54272
	ds_read_b128 v[226:229], v221 offset:55296
	ds_read_b128 v[230:233], v221 offset:56320
	global_load_lds_dwordx4 v0, s[10:11]
	s_add_i32 m0, m0, 0x2000
	s_nop 0
	global_load_lds_dwordx4 v180, s[10:11]
	s_add_i32 m0, s43, s76
	s_add_u32 s10, s100, 0x80
	s_addc_u32 s11, s101, 0
	global_load_lds_dwordx4 v0, s[10:11]
	s_add_i32 m0, m0, 0x2000
	s_nop 0
	global_load_lds_dwordx4 v180, s[10:11]
	s_mov_b32 m0, s49
	s_add_u32 s10, s22, 0x80
	s_addc_u32 s11, s23, 0
	global_load_lds_dwordx4 v176, s[10:11]
	s_mov_b32 m0, s72
	s_nop 0
	global_load_lds_dwordx4 v178, s[10:11]
	s_waitcnt vmcnt(8)
	s_waitcnt lgkmcnt(0)
	s_barrier
	s_setprio 1
	s_waitcnt lgkmcnt(0)
	v_mfma_f32_16x16x32_bf16 v[62:65], v[130:133], v[162:165], v[62:65]
	v_mfma_f32_16x16x32_bf16 v[54:57], v[138:141], v[162:165], v[54:57]
	v_mfma_f32_16x16x32_bf16 v[46:49], v[130:133], v[192:195], v[46:49]
	v_mfma_f32_16x16x32_bf16 v[38:41], v[138:141], v[192:195], v[38:41]
	v_mfma_f32_16x16x32_bf16 v[30:33], v[130:133], v[200:203], v[30:33]
	v_mfma_f32_16x16x32_bf16 v[22:25], v[138:141], v[200:203], v[22:25]
	v_mfma_f32_16x16x32_bf16 v[14:17], v[130:133], v[226:229], v[14:17]
	v_mfma_f32_16x16x32_bf16 v[6:9], v[138:141], v[226:229], v[6:9]
	v_mfma_f32_16x16x32_bf16 v[62:65], v[134:137], v[188:191], v[62:65]
	v_mfma_f32_16x16x32_bf16 v[54:57], v[142:145], v[188:191], v[54:57]
	v_mfma_f32_16x16x32_bf16 v[46:49], v[134:137], v[196:199], v[46:49]
	v_mfma_f32_16x16x32_bf16 v[38:41], v[142:145], v[196:199], v[38:41]
	v_mfma_f32_16x16x32_bf16 v[30:33], v[134:137], v[222:225], v[30:33]
	v_mfma_f32_16x16x32_bf16 v[22:25], v[142:145], v[222:225], v[22:25]
	v_mfma_f32_16x16x32_bf16 v[14:17], v[134:137], v[230:233], v[14:17]
	v_mfma_f32_16x16x32_bf16 v[6:9], v[142:145], v[230:233], v[6:9]
	s_setprio 0
	s_setprio 1
	v_mfma_f32_16x16x32_bf16 v[58:61], v[146:149], v[162:165], v[58:61]
	v_mfma_f32_16x16x32_bf16 v[50:53], v[154:157], v[162:165], v[50:53]
	v_mfma_f32_16x16x32_bf16 v[42:45], v[146:149], v[192:195], v[42:45]
	v_mfma_f32_16x16x32_bf16 v[34:37], v[154:157], v[192:195], v[34:37]
	v_mfma_f32_16x16x32_bf16 v[26:29], v[146:149], v[200:203], v[26:29]
	v_mfma_f32_16x16x32_bf16 v[18:21], v[154:157], v[200:203], v[18:21]
	v_mfma_f32_16x16x32_bf16 v[10:13], v[146:149], v[226:229], v[10:13]
	v_mfma_f32_16x16x32_bf16 v[2:5], v[154:157], v[226:229], v[2:5]
	v_mfma_f32_16x16x32_bf16 v[58:61], v[150:153], v[188:191], v[58:61]
	v_mfma_f32_16x16x32_bf16 v[50:53], v[158:161], v[188:191], v[50:53]
	v_mfma_f32_16x16x32_bf16 v[42:45], v[150:153], v[196:199], v[42:45]
	v_mfma_f32_16x16x32_bf16 v[34:37], v[158:161], v[196:199], v[34:37]
	v_mfma_f32_16x16x32_bf16 v[26:29], v[150:153], v[222:225], v[26:29]
	v_mfma_f32_16x16x32_bf16 v[18:21], v[158:161], v[222:225], v[18:21]
	v_mfma_f32_16x16x32_bf16 v[10:13], v[150:153], v[230:233], v[10:13]
	v_mfma_f32_16x16x32_bf16 v[2:5], v[158:161], v[230:233], v[2:5]
	s_setprio 0
	s_barrier
	s_add_u32 s40, s40, 0x100
	s_addc_u32 s41, s41, 0
	s_add_u32 s24, s24, 0x100
	s_addc_u32 s25, s25, 0
	s_cmp_ge_u32 s42, s68
	s_mov_b32 s22, s42
	s_cbranch_scc0 .LBB0_662
	s_and_b64 vcc, exec, s[14:15]
	s_cbranch_vccz .LBB0_665
	s_barrier

; __global__ void __launch_bounds__(NWAVES * 64, 2) fwd_megakernel(Args args) {
	.amdhsa_kernel _Z14fwd_megakernel4Args
		.amdhsa_group_segment_fixed_size 0
		.amdhsa_private_segment_fixed_size 0
		.amdhsa_kernarg_size 424
		.amdhsa_user_sgpr_count 2
		.amdhsa_user_sgpr_dispatch_ptr 0
		.amdhsa_user_sgpr_queue_ptr 0
		.amdhsa_user_sgpr_kernarg_segment_ptr 1
		.amdhsa_user_sgpr_dispatch_id 0
		.amdhsa_user_sgpr_kernarg_preload_length 0
		.amdhsa_user_sgpr_kernarg_preload_offset 0
		.amdhsa_user_sgpr_private_segment_size 0
		.amdhsa_uses_dynamic_stack 0
		.amdhsa_enable_private_segment 0
		.amdhsa_system_sgpr_workgroup_id_x 1
		.amdhsa_system_sgpr_workgroup_id_y 0
		.amdhsa_system_sgpr_workgroup_id_z 0
		.amdhsa_system_sgpr_workgroup_info 0
		.amdhsa_system_vgpr_workitem_id 2
		.amdhsa_next_free_vgpr 251
		.amdhsa_next_free_sgpr 102
		.amdhsa_accum_offset 252
		.amdhsa_reserve_vcc 1
		.amdhsa_float_round_mode_32 0
		.amdhsa_float_round_mode_16_64 0
		.amdhsa_float_denorm_mode_32 3
		.amdhsa_float_denorm_mode_16_64 3
		.amdhsa_dx10_clamp 1
		.amdhsa_ieee_mode 1
		.amdhsa_fp16_overflow 0
		.amdhsa_tg_split 0
		.amdhsa_exception_fp_ieee_invalid_op 0
		.amdhsa_exception_fp_denorm_src 0
		.amdhsa_exception_fp_ieee_div_zero 0
		.amdhsa_exception_fp_ieee_overflow 0
		.amdhsa_exception_fp_ieee_underflow 0
		.amdhsa_exception_fp_ieee_inexact 0
		.amdhsa_exception_int_div_zero 0
	.end_amdhsa_kernel

; __global__ void __launch_bounds__(NWAVES * 64, 2) fwd_megakernel(Args args) {
amdhsa.kernels:
  - .agpr_count:     0
    .args:
      - .offset:         0
        .size:           168
        .value_kind:     by_value
      - .offset:         168
        .size:           4
        .value_kind:     hidden_block_count_x
      - .offset:         172
        .size:           4
        .value_kind:     hidden_block_count_y
      - .offset:         176
        .size:           4
        .value_kind:     hidden_block_count_z
      - .offset:         180
        .size:           2
        .value_kind:     hidden_group_size_x
      - .offset:         182
        .size:           2
        .value_kind:     hidden_group_size_y
      - .offset:         184
        .size:           2
        .value_kind:     hidden_group_size_z
      - .offset:         186
        .size:           2
        .value_kind:     hidden_remainder_x
      - .offset:         188
        .size:           2
        .value_kind:     hidden_remainder_y
      - .offset:         190
        .size:           2
        .value_kind:     hidden_remainder_z
      - .offset:         208
        .size:           8
        .value_kind:     hidden_global_offset_x
      - .offset:         216
        .size:           8
        .value_kind:     hidden_global_offset_y
      - .offset:         224
        .size:           8
        .value_kind:     hidden_global_offset_z
      - .offset:         232
        .size:           2
        .value_kind:     hidden_grid_dims
      - .offset:         256
        .size:           8
        .value_kind:     hidden_multigrid_sync_arg
      - .offset:         288
        .size:           4
        .value_kind:     hidden_dynamic_lds_size
    .group_segment_fixed_size: 0
    .kernarg_segment_align: 8
    .kernarg_segment_size: 424
    .language:       OpenCL C
    .language_version:
      - 2
      - 0
    .max_flat_workgroup_size: 512
    .name:           _Z14fwd_megakernel4Args
    .private_segment_fixed_size: 0
    .sgpr_count:     108
    .sgpr_spill_count: 180
    .symbol:         _Z14fwd_megakernel4Args.kd
    .uniform_work_group_size: 1
    .uses_dynamic_stack: false
    .vgpr_count:     251
    .vgpr_spill_count: 0
    .wavefront_size: 64
